# prep_gla<128> (HGRN2 prompt) first loop: the 16 (f,q) element load pairs hoisted ahead of the per-element blocks
# speedup vs baseline: 1.0125x; 1.0078x over previous
; DI float sigm(float x) { return __builtin_amdgcn_rcpf(1.f + __expf(-x)); }
; template <int K, bool HG>
; DI void prep_gla(LAS unsigned char* lds, const Params& P, int l, int unit) {
;     ...
;     for (int i = 0; i < NE; ++i) { const int t = t0 + TS * i; qv[i] = 0.f; kv[i] = 0.f; float lg = 0.f;
;         if (t < up.nvalid) { const size_t row = (size_t)(up.row0 + t);
;             if (HG) { const int ch = up.h * 128 + k; const float fp = P32[row * LDP + C_BF + ch]; qv[i] = P32[row * LDP + C_BQ + ch];
;                 const float f = lb + (1.f - lb) * sigm(fp); lg = __logf(fmaxf(f, 1e-30f)); kv[i] = (1.f - lb) * sigm(-fp); }
.LBB0_654:
	s_lshl_b32 s3, s28, 4
	s_and_b32 s3, s3, 0x1fc0
	s_add_u32 s82, s92, s42
	v_mov_b32_e32 v3, 0
	v_ashrrev_i32_e32 v37, 7, v0
	s_addc_u32 s83, s93, s43
	v_sub_f32_e32 v50, 1.0, v49
	v_cmp_gt_i32_e64 s[42:43], s86, v34
	v_mov_b32_e32 v2, 0
	v_mov_b32_e32 v0, v3
	s_mul_i32 s8, s3, 0x6800
	s_add_u32 s6, s82, s8
	s_addc_u32 s7, s83, 0
	s_add_u32 s6, s6, 0x1000
	s_addc_u32 s7, s7, 0
	v_mul_u32_u24_e32 v122, 0x6800, v37
	v_lshl_add_u32 v122, v38, 2, v122
	global_load_dword v74, v122, s[6:7] offset:2048
	global_load_dword v75, v122, s[6:7]
	s_add_u32 s6, s6, 0x1a000
	s_addc_u32 s7, s7, 0
	global_load_dword v76, v122, s[6:7] offset:2048
	global_load_dword v77, v122, s[6:7]
	s_add_u32 s6, s6, 0x1a000
	s_addc_u32 s7, s7, 0
	global_load_dword v78, v122, s[6:7] offset:2048
	global_load_dword v79, v122, s[6:7]
	s_add_u32 s6, s6, 0x1a000
	s_addc_u32 s7, s7, 0
	global_load_dword v80, v122, s[6:7] offset:2048
	global_load_dword v81, v122, s[6:7]
	s_add_u32 s6, s6, 0x1a000
	s_addc_u32 s7, s7, 0
	global_load_dword v82, v122, s[6:7] offset:2048
	global_load_dword v83, v122, s[6:7]
	s_add_u32 s6, s6, 0x1a000
	s_addc_u32 s7, s7, 0
	global_load_dword v84, v122, s[6:7] offset:2048
	global_load_dword v85, v122, s[6:7]
	s_add_u32 s6, s6, 0x1a000
	s_addc_u32 s7, s7, 0
	global_load_dword v86, v122, s[6:7] offset:2048
	global_load_dword v87, v122, s[6:7]
	s_add_u32 s6, s6, 0x1a000
	s_addc_u32 s7, s7, 0
	global_load_dword v88, v122, s[6:7] offset:2048
	global_load_dword v89, v122, s[6:7]
	s_add_u32 s6, s6, 0x1a000
	s_addc_u32 s7, s7, 0
	global_load_dword v90, v122, s[6:7] offset:2048
	global_load_dword v91, v122, s[6:7]
	s_add_u32 s6, s6, 0x1a000
	s_addc_u32 s7, s7, 0
	global_load_dword v92, v122, s[6:7] offset:2048
	global_load_dword v93, v122, s[6:7]
	s_add_u32 s6, s6, 0x1a000
	s_addc_u32 s7, s7, 0
	global_load_dword v94, v122, s[6:7] offset:2048
	global_load_dword v95, v122, s[6:7]
	s_add_u32 s6, s6, 0x1a000
	s_addc_u32 s7, s7, 0
	global_load_dword v96, v122, s[6:7] offset:2048
	global_load_dword v97, v122, s[6:7]
	s_add_u32 s6, s6, 0x1a000
	s_addc_u32 s7, s7, 0
	global_load_dword v98, v122, s[6:7] offset:2048
	global_load_dword v99, v122, s[6:7]
	s_add_u32 s6, s6, 0x1a000
	s_addc_u32 s7, s7, 0
	global_load_dword v100, v122, s[6:7] offset:2048
	global_load_dword v101, v122, s[6:7]
	s_add_u32 s6, s6, 0x1a000
	s_addc_u32 s7, s7, 0
	global_load_dword v102, v122, s[6:7] offset:2048
	global_load_dword v103, v122, s[6:7]
	s_add_u32 s6, s6, 0x1a000
	s_addc_u32 s7, s7, 0
	global_load_dword v104, v122, s[6:7] offset:2048
	global_load_dword v105, v122, s[6:7]
	s_and_saveexec_b64 s[46:47], s[42:43]
	s_cbranch_execz .LBB0_656
	v_add_u32_e32 v0, s3, v37
	v_mov_b64_e32 v[2:3], s[82:83]
	v_mad_i64_i32 v[2:3], s[6:7], v0, s76, v[2:3]
	v_lshl_add_u64 v[2:3], v[38:39], 2, v[2:3]
	v_add_co_u32_e32 v2, vcc, 0x1000, v2
	s_mov_b32 s5, 0x3f317217
	s_nop 0
	v_addc_co_u32_e32 v3, vcc, 0, v3, vcc
	s_waitcnt vmcnt(0)
	v_mov_b32_e32 v0, v74
	v_mov_b32_e32 v4, v75
	s_waitcnt vmcnt(1)
	v_mul_f32_e32 v2, 0xbfb8aa3b, v0
	v_exp_f32_e32 v2, v2
	v_mul_f32_e32 v0, 0x3fb8aa3b, v0
	v_exp_f32_e32 v0, v0
	v_add_f32_e32 v2, 1.0, v2
	v_rcp_f32_e32 v2, v2
	v_add_f32_e32 v0, 1.0, v0
	v_rcp_f32_e32 v0, v0
	v_fma_f32 v2, v50, v2, v49
	v_max_f32_e32 v2, 0xda24260, v2
	v_cmp_gt_f32_e32 vcc, s95, v2
	s_nop 1
	v_cndmask_b32_e64 v3, 0, 32, vcc
	v_ldexp_f32 v2, v2, v3
	v_log_f32_e32 v2, v2
	s_nop 0
	v_mul_f32_e32 v3, 0x3f317217, v2
	v_fma_f32 v3, v2, s5, -v3
	v_fmac_f32_e32 v3, 0x3377d1cf, v2
	s_mov_b32 s5, 0x7f800000
	v_fmac_f32_e32 v3, 0x3f317217, v2
	v_cmp_lt_f32_e64 s[44:45], |v2|, s5
	s_nop 1
	v_cndmask_b32_e64 v2, v2, v3, s[44:45]
	v_cndmask_b32_e32 v3, 0, v238, vcc
	v_sub_f32_e32 v3, v2, v3
	v_mul_f32_e32 v2, v50, v0
	s_waitcnt vmcnt(0)
	v_mov_b32_e32 v0, v4
.LBB0_656:
	s_or_b64 exec, exec, s[46:47]
	v_lshl_add_u32 v41, v36, 2, 0
	s_and_saveexec_b64 s[44:45], s[42:43]
	v_lshl_add_u32 v4, v37, 9, v41
	ds_write_b32 v4, v3
	s_or_b64 exec, exec, s[44:45]
	v_mov_b32_e32 v3, v1
	s_movk_i32 s5, 0x1e00
	v_mov_b64_e32 v[18:19], v[14:15]
	v_add_u32_e32 v40, 4, v37
	v_cmp_gt_i32_e64 s[44:45], s5, v34
	v_mov_b32_e32 v20, 0
	v_mov_b64_e32 v[16:17], v[12:13]
	v_mov_b64_e32 v[14:15], v[10:11]
	v_mov_b64_e32 v[12:13], v[8:9]
	v_mov_b64_e32 v[10:11], v[6:7]
	v_mov_b64_e32 v[8:9], v[4:5]
	v_mov_b64_e32 v[6:7], v[2:3]
	v_mov_b64_e32 v[4:5], v[0:1]
	s_and_saveexec_b64 s[48:49], s[44:45]
	s_cbranch_execz .LBB0_660
	v_add_u32_e32 v3, s3, v40
	v_mov_b64_e32 v[4:5], s[82:83]
	v_mad_i64_i32 v[4:5], s[6:7], v3, s76, v[4:5]
	v_lshl_add_u64 v[4:5], v[38:39], 2, v[4:5]
	v_add_co_u32_e32 v4, vcc, 0x1000, v4
	s_mov_b32 s5, 0x3f317217
	s_nop 0
	v_addc_co_u32_e32 v5, vcc, 0, v5, vcc
	v_mov_b32_e32 v3, v76
	v_mov_b32_e32 v20, v77
	s_waitcnt vmcnt(1)
	v_mov_b64_e32 v[18:19], v[14:15]
	v_mov_b64_e32 v[16:17], v[12:13]
	v_mov_b64_e32 v[14:15], v[10:11]
	v_mov_b64_e32 v[12:13], v[8:9]
	v_mov_b64_e32 v[10:11], v[6:7]
	v_mov_b64_e32 v[8:9], v[4:5]
	v_mov_b64_e32 v[6:7], v[2:3]
	v_mov_b64_e32 v[4:5], v[0:1]
	v_mul_f32_e32 v0, 0xbfb8aa3b, v3
	v_exp_f32_e32 v0, v0
	s_waitcnt vmcnt(0)
	v_mov_b32_e32 v5, v20
	v_add_f32_e32 v0, 1.0, v0
	v_rcp_f32_e32 v0, v0
	s_nop 0
	v_fma_f32 v0, v50, v0, v49
	v_max_f32_e32 v0, 0xda24260, v0
	v_cmp_gt_f32_e32 vcc, s95, v0
	s_nop 1
	v_cndmask_b32_e64 v6, 0, 32, vcc
	v_ldexp_f32 v0, v0, v6
	v_log_f32_e32 v0, v0
	s_nop 0
	v_mul_f32_e32 v6, 0x3f317217, v0
	v_fma_f32 v6, v0, s5, -v6
	v_fmac_f32_e32 v6, 0x3377d1cf, v0
	s_mov_b32 s5, 0x7f800000
	v_fmac_f32_e32 v6, 0x3f317217, v0
	v_cmp_lt_f32_e64 s[46:47], |v0|, s5
	s_nop 1
	v_cndmask_b32_e64 v0, v0, v6, s[46:47]
	v_cndmask_b32_e32 v6, 0, v238, vcc
	v_sub_f32_e32 v20, v0, v6
	v_mul_f32_e32 v0, 0x3fb8aa3b, v3
	v_exp_f32_e32 v0, v0
	s_nop 0
	v_add_f32_e32 v0, 1.0, v0
	v_rcp_f32_e32 v0, v0
	s_nop 0
	v_mul_f32_e32 v3, v50, v0
; DI float sigm(float x) { return __builtin_amdgcn_rcpf(1.f + __expf(-x)); }
; DI float softplus_(float x) { return fmaxf(x, 0.f) + log1pf(__expf(-fabsf(x))); }
; template <int K, bool HG>
; DI void prep_gla(LAS unsigned char* lds, const Params& P, int l, int unit) {
;     ...
;     for (int i = 0; i < NE; ++i) { const int t = t0 + TS * i; qv[i] = 0.f; kv[i] = 0.f; float lg = 0.f;
;         if (t < up.nvalid) { const size_t row = (size_t)(up.row0 + t);
;             if (HG) { const int ch = up.h * 128 + k; const float fp = P32[row * LDP + C_BF + ch]; qv[i] = P32[row * LDP + C_BQ + ch];
;                 const float f = lb + (1.f - lb) * sigm(fp); lg = __logf(fmaxf(f, 1e-30f)); kv[i] = (1.f - lb) * sigm(-fp); }
;             else { const int ch = up.h * 64 + k; qv[i] = P32[row * LDP + C_CQ + ch] * 0.125f; kv[i] = P32[row * LDP + C_CK + ch]; float x = bias;
; #pragma unroll
;                 for (int rr = 0; rr < 16; ++rr) x += cl[t * 16 + rr] * wcol[rr];
;                 lg = -softplus_(-x) * (1.f / 16.f); } }
;         if (t < TR) Gs[t * K + k] = lg; }
.LBB0_660:
	s_or_b64 exec, exec, s[48:49]
	v_lshl_add_u32 v42, v40, 9, v41
	s_and_saveexec_b64 s[46:47], s[44:45]
	ds_write_b32 v42, v20
	s_or_b64 exec, exec, s[46:47]
	s_movk_i32 s5, 0x1c00
	v_add_u32_e32 v0, 8, v37
	v_mov_b32_e32 v6, s29
	v_mov_b32_e32 v8, s29
	v_cmp_gt_i32_e64 s[46:47], s5, v34
	v_mov_b32_e32 v7, 0
	s_and_saveexec_b64 s[50:51], s[46:47]
	s_cbranch_execz .LBB0_664
	v_add_u32_e32 v8, s3, v0
	v_mov_b64_e32 v[6:7], s[82:83]
	v_mad_i64_i32 v[6:7], s[6:7], v8, s76, v[6:7]
	v_lshl_add_u64 v[6:7], v[38:39], 2, v[6:7]
	v_add_co_u32_e32 v6, vcc, 0x1000, v6
	s_mov_b32 s5, 0x3f317217
	s_nop 0
	v_addc_co_u32_e32 v7, vcc, 0, v7, vcc
	v_mov_b32_e32 v8, v78
	s_nop 0
	v_mov_b32_e32 v6, v79
	s_waitcnt vmcnt(1)
	v_mul_f32_e32 v7, 0xbfb8aa3b, v8
	v_exp_f32_e32 v7, v7
	v_mul_f32_e32 v8, 0x3fb8aa3b, v8
	v_exp_f32_e32 v8, v8
	v_add_f32_e32 v7, 1.0, v7
	v_rcp_f32_e32 v7, v7
	v_add_f32_e32 v8, 1.0, v8
	v_rcp_f32_e32 v8, v8
	v_fma_f32 v7, v50, v7, v49
	v_max_f32_e32 v7, 0xda24260, v7
	v_cmp_gt_f32_e32 vcc, s95, v7
	v_mul_f32_e32 v8, v50, v8
	s_nop 0
	v_cndmask_b32_e64 v9, 0, 32, vcc
	v_ldexp_f32 v7, v7, v9
	v_log_f32_e32 v7, v7
	s_nop 0
	v_mul_f32_e32 v9, 0x3f317217, v7
	v_fma_f32 v9, v7, s5, -v9
	v_fmac_f32_e32 v9, 0x3377d1cf, v7
	s_mov_b32 s5, 0x7f800000
	v_fmac_f32_e32 v9, 0x3f317217, v7
	v_cmp_lt_f32_e64 s[48:49], |v7|, s5
	s_nop 1
	v_cndmask_b32_e64 v7, v7, v9, s[48:49]
	v_cndmask_b32_e32 v9, 0, v238, vcc
	v_sub_f32_e32 v7, v7, v9
.LBB0_664:
	s_or_b64 exec, exec, s[50:51]
	v_lshl_add_u32 v44, v0, 9, v41
	s_and_saveexec_b64 s[48:49], s[46:47]
	ds_write_b32 v44, v7
	s_or_b64 exec, exec, s[48:49]
	s_movk_i32 s5, 0x1a00
	v_add_u32_e32 v43, 12, v37
	v_mov_b32_e32 v7, s29
	v_mov_b32_e32 v9, s29
	v_cmp_gt_i32_e64 s[48:49], s5, v34
	v_mov_b32_e32 v10, 0
	s_and_saveexec_b64 s[52:53], s[48:49]
	s_cbranch_execz .LBB0_668
	v_add_u32_e32 v7, s3, v43
	v_mov_b64_e32 v[10:11], s[82:83]
	v_mad_i64_i32 v[10:11], s[6:7], v7, s76, v[10:11]
	v_lshl_add_u64 v[10:11], v[38:39], 2, v[10:11]
	v_add_co_u32_e32 v10, vcc, 0x1000, v10
	s_mov_b32 s5, 0x3f317217
	s_nop 0
	v_addc_co_u32_e32 v11, vcc, 0, v11, vcc
	v_mov_b32_e32 v9, v80
	v_mov_b32_e32 v7, v81
	s_waitcnt vmcnt(1)
	v_mul_f32_e32 v10, 0xbfb8aa3b, v9
	v_exp_f32_e32 v10, v10
	v_mul_f32_e32 v9, 0x3fb8aa3b, v9
	v_exp_f32_e32 v9, v9
	v_add_f32_e32 v10, 1.0, v10
	v_rcp_f32_e32 v10, v10
	v_add_f32_e32 v9, 1.0, v9
	v_rcp_f32_e32 v9, v9
	v_fma_f32 v10, v50, v10, v49
	v_max_f32_e32 v10, 0xda24260, v10
	v_cmp_gt_f32_e32 vcc, s95, v10
	v_mul_f32_e32 v9, v50, v9
	s_nop 0
	v_cndmask_b32_e64 v11, 0, 32, vcc
	v_ldexp_f32 v10, v10, v11
	v_log_f32_e32 v10, v10
	s_nop 0
	v_mul_f32_e32 v11, 0x3f317217, v10
	v_fma_f32 v11, v10, s5, -v11
	v_fmac_f32_e32 v11, 0x3377d1cf, v10
	s_mov_b32 s5, 0x7f800000
	v_fmac_f32_e32 v11, 0x3f317217, v10
	v_cmp_lt_f32_e64 s[50:51], |v10|, s5
	s_nop 1
	v_cndmask_b32_e64 v10, v10, v11, s[50:51]
	v_cndmask_b32_e32 v11, 0, v238, vcc
	v_sub_f32_e32 v10, v10, v11
.LBB0_668:
	s_or_b64 exec, exec, s[52:53]
	v_lshl_add_u32 v46, v43, 9, v41
	s_and_saveexec_b64 s[50:51], s[48:49]
	ds_write_b32 v46, v10
	s_or_b64 exec, exec, s[50:51]
	s_movk_i32 s5, 0x1800
	v_add_u32_e32 v45, 16, v37
	v_mov_b32_e32 v10, s29
	v_mov_b32_e32 v12, s29
	v_cmp_gt_i32_e64 s[50:51], s5, v34
	v_mov_b32_e32 v11, 0
	s_and_saveexec_b64 s[54:55], s[50:51]
	s_cbranch_execz .LBB0_672
	v_add_u32_e32 v12, s3, v45
	v_mov_b64_e32 v[10:11], s[82:83]
	v_mad_i64_i32 v[10:11], s[6:7], v12, s76, v[10:11]
	v_lshl_add_u64 v[10:11], v[38:39], 2, v[10:11]
	v_add_co_u32_e32 v10, vcc, 0x1000, v10
	s_mov_b32 s5, 0x3f317217
	s_nop 0
	v_addc_co_u32_e32 v11, vcc, 0, v11, vcc
	v_mov_b32_e32 v12, v82
	s_nop 0
	v_mov_b32_e32 v10, v83
	s_waitcnt vmcnt(1)
	v_mul_f32_e32 v11, 0xbfb8aa3b, v12
	v_exp_f32_e32 v11, v11
	v_mul_f32_e32 v12, 0x3fb8aa3b, v12
	v_exp_f32_e32 v12, v12
	v_add_f32_e32 v11, 1.0, v11
	v_rcp_f32_e32 v11, v11
	v_add_f32_e32 v12, 1.0, v12
	v_rcp_f32_e32 v12, v12
	v_fma_f32 v11, v50, v11, v49
	v_max_f32_e32 v11, 0xda24260, v11
	v_cmp_gt_f32_e32 vcc, s95, v11
	v_mul_f32_e32 v12, v50, v12
	s_nop 0
	v_cndmask_b32_e64 v13, 0, 32, vcc
	v_ldexp_f32 v11, v11, v13
	v_log_f32_e32 v11, v11
	s_nop 0
	v_mul_f32_e32 v13, 0x3f317217, v11
	v_fma_f32 v13, v11, s5, -v13
	v_fmac_f32_e32 v13, 0x3377d1cf, v11
	s_mov_b32 s5, 0x7f800000
	v_fmac_f32_e32 v13, 0x3f317217, v11
	v_cmp_lt_f32_e64 s[52:53], |v11|, s5
	s_nop 1
	v_cndmask_b32_e64 v11, v11, v13, s[52:53]
	v_cndmask_b32_e32 v13, 0, v238, vcc
	v_sub_f32_e32 v11, v11, v13
.LBB0_672:
	s_or_b64 exec, exec, s[54:55]
	v_lshl_add_u32 v48, v45, 9, v41
	s_and_saveexec_b64 s[52:53], s[50:51]
	ds_write_b32 v48, v11
	s_or_b64 exec, exec, s[52:53]
	s_movk_i32 s5, 0x1600
	v_add_u32_e32 v47, 20, v37
	v_mov_b32_e32 v11, s29
	v_mov_b32_e32 v13, s29
	v_cmp_gt_i32_e64 s[52:53], s5, v34
	v_mov_b32_e32 v14, 0
	s_and_saveexec_b64 s[56:57], s[52:53]
	s_cbranch_execz .LBB0_676
	v_add_u32_e32 v11, s3, v47
	v_mov_b64_e32 v[14:15], s[82:83]
	v_mad_i64_i32 v[14:15], s[6:7], v11, s76, v[14:15]
	v_lshl_add_u64 v[14:15], v[38:39], 2, v[14:15]
	v_add_co_u32_e32 v14, vcc, 0x1000, v14
	s_mov_b32 s5, 0x3f317217
	s_nop 0
	v_addc_co_u32_e32 v15, vcc, 0, v15, vcc
	v_mov_b32_e32 v13, v84
	v_mov_b32_e32 v11, v85
	s_waitcnt vmcnt(1)
	v_mul_f32_e32 v14, 0xbfb8aa3b, v13
	v_exp_f32_e32 v14, v14
	v_mul_f32_e32 v13, 0x3fb8aa3b, v13
	v_exp_f32_e32 v13, v13
	v_add_f32_e32 v14, 1.0, v14
	v_rcp_f32_e32 v14, v14
	v_add_f32_e32 v13, 1.0, v13
	v_rcp_f32_e32 v13, v13
	v_fma_f32 v14, v50, v14, v49
	v_max_f32_e32 v14, 0xda24260, v14
	v_cmp_gt_f32_e32 vcc, s95, v14
	v_mul_f32_e32 v13, v50, v13
	s_nop 0
	v_cndmask_b32_e64 v15, 0, 32, vcc
	v_ldexp_f32 v14, v14, v15
	v_log_f32_e32 v14, v14
	s_nop 0
	v_mul_f32_e32 v15, 0x3f317217, v14
	v_fma_f32 v15, v14, s5, -v15
	v_fmac_f32_e32 v15, 0x3377d1cf, v14
	s_mov_b32 s5, 0x7f800000
	v_fmac_f32_e32 v15, 0x3f317217, v14
	v_cmp_lt_f32_e64 s[54:55], |v14|, s5
	s_nop 1
	v_cndmask_b32_e64 v14, v14, v15, s[54:55]
	v_cndmask_b32_e32 v15, 0, v238, vcc
	v_sub_f32_e32 v14, v14, v15
; DI float sigm(float x) { return __builtin_amdgcn_rcpf(1.f + __expf(-x)); }
; DI float softplus_(float x) { return fmaxf(x, 0.f) + log1pf(__expf(-fabsf(x))); }
; template <int K, bool HG>
; DI void prep_gla(LAS unsigned char* lds, const Params& P, int l, int unit) {
;     ...
;     for (int i = 0; i < NE; ++i) { const int t = t0 + TS * i; qv[i] = 0.f; kv[i] = 0.f; float lg = 0.f;
;         if (t < up.nvalid) { const size_t row = (size_t)(up.row0 + t);
;             if (HG) { const int ch = up.h * 128 + k; const float fp = P32[row * LDP + C_BF + ch]; qv[i] = P32[row * LDP + C_BQ + ch];
;                 const float f = lb + (1.f - lb) * sigm(fp); lg = __logf(fmaxf(f, 1e-30f)); kv[i] = (1.f - lb) * sigm(-fp); }
;             else { const int ch = up.h * 64 + k; qv[i] = P32[row * LDP + C_CQ + ch] * 0.125f; kv[i] = P32[row * LDP + C_CK + ch]; float x = bias;
; #pragma unroll
;                 for (int rr = 0; rr < 16; ++rr) x += cl[t * 16 + rr] * wcol[rr];
;                 lg = -softplus_(-x) * (1.f / 16.f); } }
;         if (t < TR) Gs[t * K + k] = lg; }
.LBB0_676:
	s_or_b64 exec, exec, s[56:57]
	v_lshl_add_u32 v52, v47, 9, v41
	s_and_saveexec_b64 s[54:55], s[52:53]
	ds_write_b32 v52, v14
	s_or_b64 exec, exec, s[54:55]
	s_movk_i32 s5, 0x1400
	v_add_u32_e32 v51, 24, v37
	v_mov_b32_e32 v14, s29
	v_mov_b32_e32 v16, s29
	v_cmp_gt_i32_e64 s[54:55], s5, v34
	v_mov_b32_e32 v15, 0
	s_and_saveexec_b64 s[58:59], s[54:55]
	s_cbranch_execz .LBB0_680
	v_add_u32_e32 v16, s3, v51
	v_mov_b64_e32 v[14:15], s[82:83]
	v_mad_i64_i32 v[14:15], s[6:7], v16, s76, v[14:15]
	v_lshl_add_u64 v[14:15], v[38:39], 2, v[14:15]
	v_add_co_u32_e32 v14, vcc, 0x1000, v14
	s_mov_b32 s5, 0x3f317217
	s_nop 0
	v_addc_co_u32_e32 v15, vcc, 0, v15, vcc
	v_mov_b32_e32 v16, v86
	s_nop 0
	v_mov_b32_e32 v14, v87
	s_waitcnt vmcnt(1)
	v_mul_f32_e32 v15, 0xbfb8aa3b, v16
	v_exp_f32_e32 v15, v15
	v_mul_f32_e32 v16, 0x3fb8aa3b, v16
	v_exp_f32_e32 v16, v16
	v_add_f32_e32 v15, 1.0, v15
	v_rcp_f32_e32 v15, v15
	v_add_f32_e32 v16, 1.0, v16
	v_rcp_f32_e32 v16, v16
	v_fma_f32 v15, v50, v15, v49
	v_max_f32_e32 v15, 0xda24260, v15
	v_cmp_gt_f32_e32 vcc, s95, v15
	v_mul_f32_e32 v16, v50, v16
	s_nop 0
	v_cndmask_b32_e64 v17, 0, 32, vcc
	v_ldexp_f32 v15, v15, v17
	v_log_f32_e32 v15, v15
	s_nop 0
	v_mul_f32_e32 v17, 0x3f317217, v15
	v_fma_f32 v17, v15, s5, -v17
	v_fmac_f32_e32 v17, 0x3377d1cf, v15
	s_mov_b32 s5, 0x7f800000
	v_fmac_f32_e32 v17, 0x3f317217, v15
	v_cmp_lt_f32_e64 s[56:57], |v15|, s5
	s_nop 1
	v_cndmask_b32_e64 v15, v15, v17, s[56:57]
	v_cndmask_b32_e32 v17, 0, v238, vcc
	v_sub_f32_e32 v15, v15, v17
.LBB0_680:
	s_or_b64 exec, exec, s[58:59]
	v_lshl_add_u32 v54, v51, 9, v41
	s_and_saveexec_b64 s[56:57], s[54:55]
	ds_write_b32 v54, v15
	s_or_b64 exec, exec, s[56:57]
	s_movk_i32 s5, 0x1200
	v_add_u32_e32 v53, 28, v37
	v_mov_b32_e32 v15, s29
	v_mov_b32_e32 v17, s29
	v_cmp_gt_i32_e64 s[56:57], s5, v34
	v_mov_b32_e32 v18, 0
	s_and_saveexec_b64 s[60:61], s[56:57]
	s_cbranch_execz .LBB0_684
	v_add_u32_e32 v15, s3, v53
	v_mov_b64_e32 v[18:19], s[82:83]
	v_mad_i64_i32 v[18:19], s[6:7], v15, s76, v[18:19]
	v_lshl_add_u64 v[18:19], v[38:39], 2, v[18:19]
	v_add_co_u32_e32 v18, vcc, 0x1000, v18
	s_mov_b32 s5, 0x3f317217
	s_nop 0
	v_addc_co_u32_e32 v19, vcc, 0, v19, vcc
	v_mov_b32_e32 v17, v88
	v_mov_b32_e32 v15, v89
	s_waitcnt vmcnt(1)
	v_mul_f32_e32 v18, 0xbfb8aa3b, v17
	v_exp_f32_e32 v18, v18
	v_mul_f32_e32 v17, 0x3fb8aa3b, v17
	v_exp_f32_e32 v17, v17
	v_add_f32_e32 v18, 1.0, v18
	v_rcp_f32_e32 v18, v18
	v_add_f32_e32 v17, 1.0, v17
	v_rcp_f32_e32 v17, v17
	v_fma_f32 v18, v50, v18, v49
	v_max_f32_e32 v18, 0xda24260, v18
	v_cmp_gt_f32_e32 vcc, s95, v18
	v_mul_f32_e32 v17, v50, v17
	s_nop 0
	v_cndmask_b32_e64 v19, 0, 32, vcc
	v_ldexp_f32 v18, v18, v19
	v_log_f32_e32 v18, v18
	s_nop 0
	v_mul_f32_e32 v19, 0x3f317217, v18
	v_fma_f32 v19, v18, s5, -v19
	v_fmac_f32_e32 v19, 0x3377d1cf, v18
	s_mov_b32 s5, 0x7f800000
	v_fmac_f32_e32 v19, 0x3f317217, v18
	v_cmp_lt_f32_e64 s[58:59], |v18|, s5
	s_nop 1
	v_cndmask_b32_e64 v18, v18, v19, s[58:59]
	v_cndmask_b32_e32 v19, 0, v238, vcc
	v_sub_f32_e32 v18, v18, v19
.LBB0_684:
	s_or_b64 exec, exec, s[60:61]
	v_lshl_add_u32 v56, v53, 9, v41
	s_and_saveexec_b64 s[58:59], s[56:57]
	ds_write_b32 v56, v18
	s_or_b64 exec, exec, s[58:59]
	v_add_u32_e32 v55, 32, v37
	v_mov_b32_e32 v18, s29
	v_mov_b32_e32 v20, s29
	v_cmp_gt_i32_e64 s[58:59], s88, v34
	v_mov_b32_e32 v19, 0
	s_and_saveexec_b64 s[62:63], s[58:59]
	s_cbranch_execz .LBB0_688
	v_add_u32_e32 v20, s3, v55
	v_mov_b64_e32 v[18:19], s[82:83]
	v_mad_i64_i32 v[18:19], s[6:7], v20, s76, v[18:19]
	v_lshl_add_u64 v[18:19], v[38:39], 2, v[18:19]
	v_add_co_u32_e32 v18, vcc, 0x1000, v18
	s_mov_b32 s5, 0x3f317217
	s_nop 0
	v_addc_co_u32_e32 v19, vcc, 0, v19, vcc
	v_mov_b32_e32 v20, v90
	s_nop 0
	v_mov_b32_e32 v18, v91
	s_waitcnt vmcnt(1)
	v_mul_f32_e32 v19, 0xbfb8aa3b, v20
	v_exp_f32_e32 v19, v19
	v_mul_f32_e32 v20, 0x3fb8aa3b, v20
	v_exp_f32_e32 v20, v20
	v_add_f32_e32 v19, 1.0, v19
	v_rcp_f32_e32 v19, v19
	v_add_f32_e32 v20, 1.0, v20
	v_rcp_f32_e32 v20, v20
	v_fma_f32 v19, v50, v19, v49
	v_max_f32_e32 v19, 0xda24260, v19
	v_cmp_gt_f32_e32 vcc, s95, v19
	v_mul_f32_e32 v20, v50, v20
	s_nop 0
	v_cndmask_b32_e64 v21, 0, 32, vcc
	v_ldexp_f32 v19, v19, v21
	v_log_f32_e32 v19, v19
	s_nop 0
	v_mul_f32_e32 v21, 0x3f317217, v19
	v_fma_f32 v21, v19, s5, -v21
	v_fmac_f32_e32 v21, 0x3377d1cf, v19
	s_mov_b32 s5, 0x7f800000
	v_fmac_f32_e32 v21, 0x3f317217, v19
	v_cmp_lt_f32_e64 s[60:61], |v19|, s5
	s_nop 1
	v_cndmask_b32_e64 v19, v19, v21, s[60:61]
	v_cndmask_b32_e32 v21, 0, v238, vcc
	v_sub_f32_e32 v19, v19, v21
.LBB0_688:
	s_or_b64 exec, exec, s[62:63]
	v_lshl_add_u32 v58, v55, 9, v41
	s_and_saveexec_b64 s[60:61], s[58:59]
	ds_write_b32 v58, v19
	s_or_b64 exec, exec, s[60:61]
	s_movk_i32 s5, 0xe00
	v_add_u32_e32 v57, 36, v37
	v_mov_b32_e32 v19, s29
	v_mov_b32_e32 v21, s29
	v_cmp_gt_i32_e64 s[60:61], s5, v34
	v_mov_b32_e32 v22, 0
	s_and_saveexec_b64 s[64:65], s[60:61]
	s_cbranch_execz .LBB0_692
	v_add_u32_e32 v19, s3, v57
	v_mov_b64_e32 v[22:23], s[82:83]
	v_mad_i64_i32 v[22:23], s[6:7], v19, s76, v[22:23]
	v_lshl_add_u64 v[22:23], v[38:39], 2, v[22:23]
	v_add_co_u32_e32 v22, vcc, 0x1000, v22
	s_mov_b32 s5, 0x3f317217
	s_nop 0
	v_addc_co_u32_e32 v23, vcc, 0, v23, vcc
	v_mov_b32_e32 v21, v92
	v_mov_b32_e32 v19, v93
	s_waitcnt vmcnt(1)
	v_mul_f32_e32 v22, 0xbfb8aa3b, v21
	v_exp_f32_e32 v22, v22
	v_mul_f32_e32 v21, 0x3fb8aa3b, v21
	v_exp_f32_e32 v21, v21
	v_add_f32_e32 v22, 1.0, v22
	v_rcp_f32_e32 v22, v22
	v_add_f32_e32 v21, 1.0, v21
	v_rcp_f32_e32 v21, v21
	v_fma_f32 v22, v50, v22, v49
	v_max_f32_e32 v22, 0xda24260, v22
	v_cmp_gt_f32_e32 vcc, s95, v22
	v_mul_f32_e32 v21, v50, v21
	s_nop 0
	v_cndmask_b32_e64 v23, 0, 32, vcc
	v_ldexp_f32 v22, v22, v23
	v_log_f32_e32 v22, v22
	s_nop 0
	v_mul_f32_e32 v23, 0x3f317217, v22
	v_fma_f32 v23, v22, s5, -v23
	v_fmac_f32_e32 v23, 0x3377d1cf, v22
	s_mov_b32 s5, 0x7f800000
	v_fmac_f32_e32 v23, 0x3f317217, v22
	v_cmp_lt_f32_e64 s[62:63], |v22|, s5
	s_nop 1
	v_cndmask_b32_e64 v22, v22, v23, s[62:63]
	v_cndmask_b32_e32 v23, 0, v238, vcc
	v_sub_f32_e32 v22, v22, v23
; DI float sigm(float x) { return __builtin_amdgcn_rcpf(1.f + __expf(-x)); }
; DI float softplus_(float x) { return fmaxf(x, 0.f) + log1pf(__expf(-fabsf(x))); }
; template <int K, bool HG>
; DI void prep_gla(LAS unsigned char* lds, const Params& P, int l, int unit) {
;     ...
;     for (int i = 0; i < NE; ++i) { const int t = t0 + TS * i; qv[i] = 0.f; kv[i] = 0.f; float lg = 0.f;
;         if (t < up.nvalid) { const size_t row = (size_t)(up.row0 + t);
;             if (HG) { const int ch = up.h * 128 + k; const float fp = P32[row * LDP + C_BF + ch]; qv[i] = P32[row * LDP + C_BQ + ch];
;                 const float f = lb + (1.f - lb) * sigm(fp); lg = __logf(fmaxf(f, 1e-30f)); kv[i] = (1.f - lb) * sigm(-fp); }
;             else { const int ch = up.h * 64 + k; qv[i] = P32[row * LDP + C_CQ + ch] * 0.125f; kv[i] = P32[row * LDP + C_CK + ch]; float x = bias;
; #pragma unroll
;                 for (int rr = 0; rr < 16; ++rr) x += cl[t * 16 + rr] * wcol[rr];
;                 lg = -softplus_(-x) * (1.f / 16.f); } }
;         if (t < TR) Gs[t * K + k] = lg; }
.LBB0_692:
	s_or_b64 exec, exec, s[64:65]
	v_lshl_add_u32 v60, v57, 9, v41
	s_and_saveexec_b64 s[62:63], s[60:61]
	ds_write_b32 v60, v22
	s_or_b64 exec, exec, s[62:63]
	s_movk_i32 s5, 0xc00
	v_add_u32_e32 v59, 40, v37
	v_mov_b32_e32 v22, s29
	v_mov_b32_e32 v24, s29
	v_cmp_gt_i32_e64 s[62:63], s5, v34
	v_mov_b32_e32 v23, 0
	s_and_saveexec_b64 s[66:67], s[62:63]
	s_cbranch_execz .LBB0_696
	v_add_u32_e32 v24, s3, v59
	v_mov_b64_e32 v[22:23], s[82:83]
	v_mad_i64_i32 v[22:23], s[6:7], v24, s76, v[22:23]
	v_lshl_add_u64 v[22:23], v[38:39], 2, v[22:23]
	v_add_co_u32_e32 v22, vcc, 0x1000, v22
	s_mov_b32 s5, 0x3f317217
	s_nop 0
	v_addc_co_u32_e32 v23, vcc, 0, v23, vcc
	v_mov_b32_e32 v24, v94
	s_nop 0
	v_mov_b32_e32 v22, v95
	s_waitcnt vmcnt(1)
	v_mul_f32_e32 v23, 0xbfb8aa3b, v24
	v_exp_f32_e32 v23, v23
	v_mul_f32_e32 v24, 0x3fb8aa3b, v24
	v_exp_f32_e32 v24, v24
	v_add_f32_e32 v23, 1.0, v23
	v_rcp_f32_e32 v23, v23
	v_add_f32_e32 v24, 1.0, v24
	v_rcp_f32_e32 v24, v24
	v_fma_f32 v23, v50, v23, v49
	v_max_f32_e32 v23, 0xda24260, v23
	v_cmp_gt_f32_e32 vcc, s95, v23
	v_mul_f32_e32 v24, v50, v24
	s_nop 0
	v_cndmask_b32_e64 v25, 0, 32, vcc
	v_ldexp_f32 v23, v23, v25
	v_log_f32_e32 v23, v23
	s_nop 0
	v_mul_f32_e32 v25, 0x3f317217, v23
	v_fma_f32 v25, v23, s5, -v25
	v_fmac_f32_e32 v25, 0x3377d1cf, v23
	s_mov_b32 s5, 0x7f800000
	v_fmac_f32_e32 v25, 0x3f317217, v23
	v_cmp_lt_f32_e64 s[64:65], |v23|, s5
	s_nop 1
	v_cndmask_b32_e64 v23, v23, v25, s[64:65]
	v_cndmask_b32_e32 v25, 0, v238, vcc
	v_sub_f32_e32 v23, v23, v25
.LBB0_696:
	s_or_b64 exec, exec, s[66:67]
	v_lshl_add_u32 v62, v59, 9, v41
	s_and_saveexec_b64 s[64:65], s[62:63]
	ds_write_b32 v62, v23
	s_or_b64 exec, exec, s[64:65]
	s_movk_i32 s5, 0xa00
	v_add_u32_e32 v61, 44, v37
	v_mov_b32_e32 v23, s29
	v_mov_b32_e32 v25, s29
	v_cmp_gt_i32_e64 s[64:65], s5, v34
	v_mov_b32_e32 v26, 0
	s_and_saveexec_b64 s[68:69], s[64:65]
	s_cbranch_execz .LBB0_700
	v_add_u32_e32 v23, s3, v61
	v_mov_b64_e32 v[26:27], s[82:83]
	v_mad_i64_i32 v[26:27], s[6:7], v23, s76, v[26:27]
	v_lshl_add_u64 v[26:27], v[38:39], 2, v[26:27]
	v_add_co_u32_e32 v26, vcc, 0x1000, v26
	s_mov_b32 s5, 0x3f317217
	s_nop 0
	v_addc_co_u32_e32 v27, vcc, 0, v27, vcc
	v_mov_b32_e32 v25, v96
	v_mov_b32_e32 v23, v97
	s_waitcnt vmcnt(1)
	v_mul_f32_e32 v26, 0xbfb8aa3b, v25
	v_exp_f32_e32 v26, v26
	v_mul_f32_e32 v25, 0x3fb8aa3b, v25
	v_exp_f32_e32 v25, v25
	v_add_f32_e32 v26, 1.0, v26
	v_rcp_f32_e32 v26, v26
	v_add_f32_e32 v25, 1.0, v25
	v_rcp_f32_e32 v25, v25
	v_fma_f32 v26, v50, v26, v49
	v_max_f32_e32 v26, 0xda24260, v26
	v_cmp_gt_f32_e32 vcc, s95, v26
	v_mul_f32_e32 v25, v50, v25
	s_nop 0
	v_cndmask_b32_e64 v27, 0, 32, vcc
	v_ldexp_f32 v26, v26, v27
	v_log_f32_e32 v26, v26
	s_nop 0
	v_mul_f32_e32 v27, 0x3f317217, v26
	v_fma_f32 v27, v26, s5, -v27
	v_fmac_f32_e32 v27, 0x3377d1cf, v26
	s_mov_b32 s5, 0x7f800000
	v_fmac_f32_e32 v27, 0x3f317217, v26
	v_cmp_lt_f32_e64 s[66:67], |v26|, s5
	s_nop 1
	v_cndmask_b32_e64 v26, v26, v27, s[66:67]
	v_cndmask_b32_e32 v27, 0, v238, vcc
	v_sub_f32_e32 v26, v26, v27
.LBB0_700:
	s_or_b64 exec, exec, s[68:69]
	v_lshl_add_u32 v64, v61, 9, v41
	s_and_saveexec_b64 s[66:67], s[64:65]
	ds_write_b32 v64, v26
	s_or_b64 exec, exec, s[66:67]
	s_movk_i32 s5, 0x800
	v_add_u32_e32 v63, 48, v37
	v_mov_b32_e32 v26, s29
	v_mov_b32_e32 v28, s29
	v_cmp_gt_i32_e64 s[66:67], s5, v34
	v_mov_b32_e32 v27, 0
	s_and_saveexec_b64 s[70:71], s[66:67]
	s_cbranch_execz .LBB0_704
	v_add_u32_e32 v28, s3, v63
	v_mov_b64_e32 v[26:27], s[82:83]
	v_mad_i64_i32 v[26:27], s[6:7], v28, s76, v[26:27]
	v_lshl_add_u64 v[26:27], v[38:39], 2, v[26:27]
	v_add_co_u32_e32 v26, vcc, 0x1000, v26
	s_mov_b32 s5, 0x3f317217
	s_nop 0
	v_addc_co_u32_e32 v27, vcc, 0, v27, vcc
	v_mov_b32_e32 v28, v98
	s_nop 0
	v_mov_b32_e32 v26, v99
	s_waitcnt vmcnt(1)
	v_mul_f32_e32 v27, 0xbfb8aa3b, v28
	v_exp_f32_e32 v27, v27
	v_mul_f32_e32 v28, 0x3fb8aa3b, v28
	v_exp_f32_e32 v28, v28
	v_add_f32_e32 v27, 1.0, v27
	v_rcp_f32_e32 v27, v27
	v_add_f32_e32 v28, 1.0, v28
	v_rcp_f32_e32 v28, v28
	v_fma_f32 v27, v50, v27, v49
	v_max_f32_e32 v27, 0xda24260, v27
	v_cmp_gt_f32_e32 vcc, s95, v27
	v_mul_f32_e32 v28, v50, v28
	s_nop 0
	v_cndmask_b32_e64 v29, 0, 32, vcc
	v_ldexp_f32 v27, v27, v29
	v_log_f32_e32 v27, v27
	s_nop 0
	v_mul_f32_e32 v29, 0x3f317217, v27
	v_fma_f32 v29, v27, s5, -v29
	v_fmac_f32_e32 v29, 0x3377d1cf, v27
	s_mov_b32 s5, 0x7f800000
	v_fmac_f32_e32 v29, 0x3f317217, v27
	v_cmp_lt_f32_e64 s[68:69], |v27|, s5
	s_nop 1
	v_cndmask_b32_e64 v27, v27, v29, s[68:69]
	v_cndmask_b32_e32 v29, 0, v238, vcc
	v_sub_f32_e32 v27, v27, v29
; DI float sigm(float x) { return __builtin_amdgcn_rcpf(1.f + __expf(-x)); }
; DI float softplus_(float x) { return fmaxf(x, 0.f) + log1pf(__expf(-fabsf(x))); }
; template <int K, bool HG>
; DI void prep_gla(LAS unsigned char* lds, const Params& P, int l, int unit) {
;     ...
;     for (int i = 0; i < NE; ++i) { const int t = t0 + TS * i; qv[i] = 0.f; kv[i] = 0.f; float lg = 0.f;
;         if (t < up.nvalid) { const size_t row = (size_t)(up.row0 + t);
;             if (HG) { const int ch = up.h * 128 + k; const float fp = P32[row * LDP + C_BF + ch]; qv[i] = P32[row * LDP + C_BQ + ch];
;                 const float f = lb + (1.f - lb) * sigm(fp); lg = __logf(fmaxf(f, 1e-30f)); kv[i] = (1.f - lb) * sigm(-fp); }
;             else { const int ch = up.h * 64 + k; qv[i] = P32[row * LDP + C_CQ + ch] * 0.125f; kv[i] = P32[row * LDP + C_CK + ch]; float x = bias;
; #pragma unroll
;                 for (int rr = 0; rr < 16; ++rr) x += cl[t * 16 + rr] * wcol[rr];
;                 lg = -softplus_(-x) * (1.f / 16.f); } }
;         if (t < TR) Gs[t * K + k] = lg; }
.LBB0_704:
	s_or_b64 exec, exec, s[70:71]
	v_lshl_add_u32 v66, v63, 9, v41
	s_and_saveexec_b64 s[68:69], s[66:67]
	ds_write_b32 v66, v27
	s_or_b64 exec, exec, s[68:69]
	s_movk_i32 s5, 0x600
	v_add_u32_e32 v65, 52, v37
	v_mov_b32_e32 v27, s29
	v_mov_b32_e32 v29, s29
	v_cmp_gt_i32_e64 s[68:69], s5, v34
	v_mov_b32_e32 v30, 0
	s_and_saveexec_b64 s[72:73], s[68:69]
	s_cbranch_execz .LBB0_708
	v_add_u32_e32 v27, s3, v65
	v_mov_b64_e32 v[30:31], s[82:83]
	v_mad_i64_i32 v[30:31], s[6:7], v27, s76, v[30:31]
	v_lshl_add_u64 v[30:31], v[38:39], 2, v[30:31]
	v_add_co_u32_e32 v30, vcc, 0x1000, v30
	s_mov_b32 s5, 0x3f317217
	s_nop 0
	v_addc_co_u32_e32 v31, vcc, 0, v31, vcc
	v_mov_b32_e32 v29, v100
	v_mov_b32_e32 v27, v101
	s_waitcnt vmcnt(1)
	v_mul_f32_e32 v30, 0xbfb8aa3b, v29
	v_exp_f32_e32 v30, v30
	v_mul_f32_e32 v29, 0x3fb8aa3b, v29
	v_exp_f32_e32 v29, v29
	v_add_f32_e32 v30, 1.0, v30
	v_rcp_f32_e32 v30, v30
	v_add_f32_e32 v29, 1.0, v29
	v_rcp_f32_e32 v29, v29
	v_fma_f32 v30, v50, v30, v49
	v_max_f32_e32 v30, 0xda24260, v30
	v_cmp_gt_f32_e32 vcc, s95, v30
	v_mul_f32_e32 v29, v50, v29
	s_nop 0
	v_cndmask_b32_e64 v31, 0, 32, vcc
	v_ldexp_f32 v30, v30, v31
	v_log_f32_e32 v30, v30
	s_nop 0
	v_mul_f32_e32 v31, 0x3f317217, v30
	v_fma_f32 v31, v30, s5, -v31
	v_fmac_f32_e32 v31, 0x3377d1cf, v30
	s_mov_b32 s5, 0x7f800000
	v_fmac_f32_e32 v31, 0x3f317217, v30
	v_cmp_lt_f32_e64 s[70:71], |v30|, s5
	s_nop 1
	v_cndmask_b32_e64 v30, v30, v31, s[70:71]
	v_cndmask_b32_e32 v31, 0, v238, vcc
	v_sub_f32_e32 v30, v30, v31
.LBB0_708:
	s_or_b64 exec, exec, s[72:73]
	v_lshl_add_u32 v68, v65, 9, v41
	s_and_saveexec_b64 s[70:71], s[68:69]
	ds_write_b32 v68, v30
	s_or_b64 exec, exec, s[70:71]
	s_movk_i32 s5, 0x400
	v_add_u32_e32 v67, 56, v37
	v_mov_b32_e32 v30, s29
	v_mov_b32_e32 v32, s29
	v_cmp_gt_i32_e64 s[70:71], s5, v34
	v_mov_b32_e32 v31, 0
	s_and_saveexec_b64 s[84:85], s[70:71]
	s_cbranch_execz .LBB0_712
	v_add_u32_e32 v32, s3, v67
	v_mov_b64_e32 v[30:31], s[82:83]
	v_mad_i64_i32 v[30:31], s[6:7], v32, s76, v[30:31]
	v_lshl_add_u64 v[30:31], v[38:39], 2, v[30:31]
	v_add_co_u32_e32 v30, vcc, 0x1000, v30
	s_mov_b32 s5, 0x3f317217
	s_nop 0
	v_addc_co_u32_e32 v31, vcc, 0, v31, vcc
	v_mov_b32_e32 v32, v102
	s_nop 0
	v_mov_b32_e32 v30, v103
	s_waitcnt vmcnt(1)
	v_mul_f32_e32 v31, 0xbfb8aa3b, v32
	v_exp_f32_e32 v31, v31
	v_mul_f32_e32 v32, 0x3fb8aa3b, v32
	v_exp_f32_e32 v32, v32
	v_add_f32_e32 v31, 1.0, v31
	v_rcp_f32_e32 v31, v31
	v_add_f32_e32 v32, 1.0, v32
	v_rcp_f32_e32 v32, v32
	v_fma_f32 v31, v50, v31, v49
	v_max_f32_e32 v31, 0xda24260, v31
	v_cmp_gt_f32_e32 vcc, s95, v31
	v_mul_f32_e32 v32, v50, v32
	s_nop 0
	v_cndmask_b32_e64 v33, 0, 32, vcc
	v_ldexp_f32 v31, v31, v33
	v_log_f32_e32 v31, v31
	s_nop 0
	v_mul_f32_e32 v33, 0x3f317217, v31
	v_fma_f32 v33, v31, s5, -v33
	v_fmac_f32_e32 v33, 0x3377d1cf, v31
	s_mov_b32 s5, 0x7f800000
	v_fmac_f32_e32 v33, 0x3f317217, v31
	v_cmp_lt_f32_e64 s[72:73], |v31|, s5
	s_nop 1
	v_cndmask_b32_e64 v31, v31, v33, s[72:73]
	v_cndmask_b32_e32 v33, 0, v238, vcc
	v_sub_f32_e32 v31, v31, v33
.LBB0_712:
	s_or_b64 exec, exec, s[84:85]
	v_lshl_add_u32 v70, v67, 9, v41
	s_and_saveexec_b64 s[72:73], s[70:71]
	ds_write_b32 v70, v31
	s_or_b64 exec, exec, s[72:73]
	s_movk_i32 s5, 0x200
	v_add_u32_e32 v69, 60, v37
	v_mov_b32_e32 v31, s29
	v_mov_b32_e32 v33, s29
	v_cmp_gt_i32_e64 s[72:73], s5, v34
	v_mov_b32_e32 v71, 0
	s_and_saveexec_b64 s[84:85], s[72:73]
	s_cbranch_execz .LBB0_716
	v_add_u32_e32 v31, s3, v69
	v_mov_b64_e32 v[72:73], s[82:83]
	v_mad_i64_i32 v[72:73], s[6:7], v31, s76, v[72:73]
	v_lshl_add_u64 v[38:39], v[38:39], 2, v[72:73]
	v_add_co_u32_e32 v38, vcc, 0x1000, v38
	s_mov_b32 s3, 0x3f317217
	s_nop 0
	v_addc_co_u32_e32 v39, vcc, 0, v39, vcc
	v_mov_b32_e32 v33, v104
	v_mov_b32_e32 v31, v105
	s_waitcnt vmcnt(1)
	v_mul_f32_e32 v38, 0xbfb8aa3b, v33
	v_exp_f32_e32 v38, v38
	v_mul_f32_e32 v33, 0x3fb8aa3b, v33
	v_exp_f32_e32 v33, v33
	v_add_f32_e32 v38, 1.0, v38
	v_rcp_f32_e32 v38, v38
	v_add_f32_e32 v33, 1.0, v33
	v_rcp_f32_e32 v33, v33
	v_fmac_f32_e32 v49, v50, v38
	v_max_f32_e32 v38, 0xda24260, v49
	v_cmp_gt_f32_e32 vcc, s95, v38
	v_mul_f32_e32 v33, v50, v33
	s_nop 0
	v_cndmask_b32_e64 v39, 0, 32, vcc
	v_ldexp_f32 v38, v38, v39
	v_log_f32_e32 v38, v38
	v_cndmask_b32_e32 v39, 0, v238, vcc
	v_mul_f32_e32 v49, 0x3f317217, v38
	v_fma_f32 v49, v38, s3, -v49
	v_fmac_f32_e32 v49, 0x3377d1cf, v38
	s_mov_b32 s3, 0x7f800000
	v_fmac_f32_e32 v49, 0x3f317217, v38
	v_cmp_lt_f32_e64 vcc, |v38|, s3
	s_nop 1
	v_cndmask_b32_e32 v38, v38, v49, vcc
	v_sub_f32_e32 v71, v38, v39
